# S5 full tiles remapped to workgroups by carry-loop length so that the D2 / double-gMLP workgroups get the short ones
# speedup vs baseline: 1.0029x; 1.0029x over previous
.LBB0_428:
	s_mov_b32 s97, 0x2040000
	s_mov_b32 s83, 0x800000
	s_or_b64 exec, exec, s[0:1]
	s_mov_b32 s20, s89
	v_readlane_b32 s0, v255, 43
	s_barrier
	v_mbcnt_lo_u32_b32 v0, -1, 0
	v_mbcnt_hi_u32_b32 v0, -1, v0
	v_readlane_b32 s1, v255, 44
	v_and_b32_e32 v76, 63, v0
	s_and_b64 vcc, exec, s[0:1]
	v_and_b32_e32 v78, 15, v0
	v_lshrrev_b32_e32 v1, 4, v76
	v_lshrrev_b32_e32 v2, 1, v76
	v_and_b32_e32 v106, 48, v0
	v_readlane_b32 s0, v254, 39
	s_mov_b64 s[26:27], s[78:79]
	s_mul_i32 s21, s20, 0x2200
	v_lshlrev_b32_e32 v77, 1, v76
	v_cmp_lt_u32_e64 s[8:9], 31, v76
	v_and_b32_e32 v58, 48, v76
	v_and_b32_e32 v56, 8, v2
	v_lshlrev_b32_e32 v80, 2, v1
	v_lshlrev_b32_e32 v107, 3, v1
	v_mul_u32_u24_e32 v57, 0x110, v78
	v_lshlrev_b32_e32 v60, 5, v78
	v_add_u32_e32 v104, s0, v106
	v_mul_u32_u24_e32 v105, 0x210, v78
	v_or_b32_e32 v79, 16, v78
	v_or_b32_e32 v81, 32, v78
	v_or_b32_e32 v111, 48, v78
	s_mov_b32 s96, s56
	s_cbranch_vccnz .LBB0_443
	v_lshlrev_b32_e32 v0, 1, v56
	v_mov_b32_e32 v1, v195
	v_lshl_add_u64 v[0:1], s[26:27], 0, v[0:1]
	v_mov_b32_e32 v61, v195
	s_add_i32 s4, s21, 0
	s_lshl_b32 s36, s20, 1
	s_lshl_b32 s37, s56, 4
	v_lshlrev_b32_e32 v194, 3, v76
	s_lshl_b32 s38, s56, 3
	v_lshl_add_u64 v[0:1], v[0:1], 0, v[60:61]
	s_mov_b64 s[0:1], 0xf48ac00
	s_add_u32 s22, s26, 0xf482c00
	v_lshl_add_u64 v[62:63], v[0:1], 0, s[0:1]
	v_lshl_add_u64 v[0:1], s[26:27], 0, v[194:195]
	s_mov_b64 s[0:1], 0xf282c00
	s_addc_u32 s23, s27, 0
	v_lshl_add_u64 v[66:67], v[0:1], 0, s[0:1]
	v_readlane_b32 s0, v255, 29
	s_add_u32 s0, s26, s0
	v_readlane_b32 s56, v252, 18
	s_addc_u32 s1, s27, 0
	s_lshl_b32 s2, s20, 5
	v_mov_b32_e32 v59, v195
	v_readlane_b32 s57, v252, 19
	v_readlane_b32 s58, v252, 20
	v_readlane_b32 s59, v252, 21
	v_readlane_b32 s60, v252, 22
	v_readlane_b32 s61, v252, 23
	v_readlane_b32 s62, v252, 24
	v_readlane_b32 s63, v252, 25
	v_readlane_b32 s64, v252, 26
	v_readlane_b32 s65, v252, 27
	v_readlane_b32 s66, v252, 28
	v_readlane_b32 s67, v252, 29
	v_or_b32_e32 v0, s2, v78
	v_readlane_b32 s68, v252, 30
	v_readlane_b32 s69, v252, 31
	v_readlane_b32 s70, v252, 32
	v_readlane_b32 s71, v252, 33
	s_mov_b64 s[56:57], s[60:61]
	v_lshl_add_u64 v[2:3], s[0:1], 0, v[58:59]
	s_mov_b64 s[0:1], 0x9070000
	v_ashrrev_i32_e32 v1, 31, v0
	s_mov_b64 s[58:59], s[62:63]
	s_mov_b64 s[60:61], s[64:65]
	s_mov_b64 s[62:63], s[66:67]
	s_mov_b64 s[64:65], s[68:69]
	v_lshl_add_u64 v[2:3], v[2:3], 0, s[0:1]
	v_lshlrev_b64 v[4:5], 9, v[0:1]
	v_or_b32_e32 v0, 16, v0
	v_readlane_b32 s0, v255, 41
	v_ashrrev_i32_e32 v1, 31, v0
	v_readlane_b32 s1, v255, 42
	s_add_u32 s0, s64, s0
	v_lshlrev_b64 v[0:1], 9, v[0:1]
	s_addc_u32 s1, s65, s1
	v_lshl_add_u64 v[72:73], v[2:3], 0, v[0:1]
	v_lshl_add_u64 v[0:1], s[0:1], 0, v[58:59]
	s_ashr_i32 s3, s2, 31
	v_lshl_add_u64 v[74:75], s[2:3], 2, v[0:1]
	v_or_b32_e32 v0, s2, v80
	v_readlane_b32 s5, v254, 39
	v_lshl_add_u64 v[70:71], v[2:3], 0, v[4:5]
	v_lshlrev_b32_e32 v1, 1, v0
	v_or_b32_e32 v2, 16, v0
	v_add_u32_e32 v6, s4, v107
	v_add_u32_e32 v7, s4, v106
	v_lshl_add_u64 v[64:65], s[60:61], 0, v[58:59]
	v_lshlrev_b32_e32 v194, 2, v76
	v_add3_u32 v59, s5, v105, v1
	v_ashrrev_i32_e32 v1, 31, v0
	v_ashrrev_i32_e32 v3, 31, v2
	s_add_i32 s4, s4, 0x8000
	v_add_u32_e32 v108, s5, v107
	v_lshl_add_u64 v[68:69], s[94:95], 0, v[194:195]
	v_or_b32_e32 v61, 16, v78
	v_or_b32_e32 v110, 48, v78
	v_add_u32_e32 v112, 0x2100, v59
	v_add_u32_e32 v113, 0x4200, v59
	v_add_u32_e32 v114, 0x6300, v59
	v_add_u32_e32 v115, s4, v194
	v_lshlrev_b32_e32 v194, 1, v56
	v_lshlrev_b32_e32 v82, 1, v80
	v_add_u32_e32 v116, v6, v57
	v_add_u32_e32 v117, v7, v57
	v_add_u32_e32 v118, v104, v105
	v_lshlrev_b64 v[84:85], 1, v[0:1]
	v_lshlrev_b64 v[86:87], 1, v[2:3]
	s_mov_b32 s39, s82
	v_readlane_b32 s0, v253, 5
	s_nop 0
	s_cmp_lg_u32 s0, 0
	s_cbranch_scc1 .Lssm_noremap
	s_sub_i32 s0, s82, 0xfc
	s_add_i32 s39, s82, 4
	s_cmp_gt_u32 s82, 0xfb
	s_cselect_b32 s39, s0, s39
	s_and_b32 s0, s39, 7
	s_lshl_b32 s0, s0, 5
	s_lshr_b32 s39, s39, 3
	s_or_b32 s39, s39, s0
.Lssm_noremap:
	s_mov_b64 s[66:67], s[70:71]
	s_branch .LBB0_431
